# v12 + fp8 loops: MFMAs of each segment in boustrophedon order (one shared operand between consecutive MFMAs)
# speedup vs baseline: 1.0080x; 1.0080x over previous
.LBB0_1420:
	ds_read_b128 v[146:149], v138
	ds_read_b128 v[150:153], v138 offset:1024
	ds_read_b128 v[154:157], v138 offset:2048
	ds_read_b128 v[158:161], v138 offset:3072
	ds_read_b128 v[162:165], v139
	ds_read_b128 v[166:169], v139 offset:1024
	ds_read_b128 v[170:173], v139 offset:2048
	ds_read_b128 v[174:177], v139 offset:3072
	s_add_i32 s14, s73, 0xfff40080
	s_cmp_eq_u32 s60, s75
	s_cselect_b32 s76, s71, s14
	s_cselect_b32 s78, s72, s74
	s_or_b32 s77, s76, 0x80
	s_add_i32 s14, s73, 0xfffc0000
	s_mov_b32 m0, s61
	ds_read_b128 v[178:181], v140
	ds_read_b128 v[182:185], v140 offset:1024
	ds_read_b128 v[186:189], v140 offset:2048
	ds_read_b128 v[190:193], v140 offset:3072
	ds_read_b128 v[194:197], v140 offset:4096
	ds_read_b128 v[198:201], v140 offset:5120
	ds_read_b128 v[202:205], v140 offset:6144
	ds_read_b128 v[206:209], v140 offset:7168
	buffer_load_dwordx4 v136, s[16:19], s14 offen lds
	s_mov_b32 m0, s62
	s_nop 0
	buffer_load_dwordx4 v136, s[16:19], s73 offen lds
	s_waitcnt vmcnt(8)
	s_waitcnt lgkmcnt(0)
	s_setprio 1
	s_waitcnt lgkmcnt(6)
	v_mfma_f32_16x16x128_f8f6f4 v[118:121], v[146:153], v[178:185], v[118:121]
	s_barrier
	v_mfma_f32_16x16x128_f8f6f4 v[114:117], v[154:161], v[178:185], v[114:117]
	s_waitcnt lgkmcnt(4)
	v_mfma_f32_16x16x128_f8f6f4 v[126:129], v[162:169], v[178:185], v[126:129]
	v_mfma_f32_16x16x128_f8f6f4 v[122:125], v[170:177], v[178:185], v[122:125]
	v_mfma_f32_16x16x128_f8f6f4 v[98:101], v[170:177], v[186:193], v[98:101]
	v_mfma_f32_16x16x128_f8f6f4 v[106:109], v[162:169], v[186:193], v[106:109]
	v_mfma_f32_16x16x128_f8f6f4 v[102:105], v[154:161], v[186:193], v[102:105]
	v_mfma_f32_16x16x128_f8f6f4 v[110:113], v[146:153], v[186:193], v[110:113]
	s_waitcnt lgkmcnt(2)
	v_mfma_f32_16x16x128_f8f6f4 v[210:213], v[146:153], v[194:201], v[94:97]
	v_mfma_f32_16x16x128_f8f6f4 v[214:217], v[154:161], v[194:201], v[86:89]
	s_waitcnt lgkmcnt(0)
	v_mfma_f32_16x16x128_f8f6f4 v[178:181], v[162:169], v[194:201], v[90:93]
	v_mfma_f32_16x16x128_f8f6f4 v[182:185], v[170:177], v[194:201], v[82:85]
	v_mfma_f32_16x16x128_f8f6f4 v[190:193], v[170:177], v[202:209], v[66:69]
	v_mfma_f32_16x16x128_f8f6f4 v[186:189], v[162:169], v[202:209], v[74:77]
	v_mfma_f32_16x16x128_f8f6f4 v[222:225], v[154:161], v[202:209], v[70:73]
	v_mfma_f32_16x16x128_f8f6f4 v[218:221], v[146:153], v[202:209], v[78:81]
	s_setprio 0
	s_barrier
	s_mov_b32 m0, s31
	s_mov_b32 s14, s18
	s_mov_b32 s15, s19
	s_nop 1
	ds_read_b128 v[66:69], v140 offset:16384
	ds_read_b128 v[70:73], v140 offset:17408
	ds_read_b128 v[74:77], v140 offset:18432
	ds_read_b128 v[78:81], v140 offset:19456
	ds_read_b128 v[82:85], v140 offset:20480
	ds_read_b128 v[86:89], v140 offset:21504
	ds_read_b128 v[90:93], v140 offset:22528
	ds_read_b128 v[94:97], v140 offset:23552
	buffer_load_dwordx4 v137, s[12:15], s78 offen lds
	s_add_i32 s79, s78, 0x40000
	s_mov_b32 m0, s46
	s_nop 0
	buffer_load_dwordx4 v137, s[12:15], s79 offen lds
	s_add_i32 s79, s78, 0x80000
	s_mov_b32 m0, s47
	s_nop 0
	buffer_load_dwordx4 v137, s[12:15], s79 offen lds
	s_add_i32 s79, s78, 0xc0000
	s_mov_b32 m0, s48
	s_nop 0
	buffer_load_dwordx4 v137, s[12:15], s79 offen lds
	s_mov_b32 m0, s30
	s_add_i32 s79, s76, 0x40000
	buffer_load_dwordx4 v136, s[16:19], s76 offen lds
	s_mov_b32 m0, s49
	s_nop 0
	buffer_load_dwordx4 v136, s[16:19], s79 offen lds
	s_waitcnt vmcnt(8)
	s_waitcnt lgkmcnt(0)
	s_setprio 1
	s_waitcnt lgkmcnt(6)
	v_mfma_f32_16x16x128_f8f6f4 v[62:65], v[146:153], v[66:73], v[62:65]
	s_barrier
	v_mfma_f32_16x16x128_f8f6f4 v[54:57], v[154:161], v[66:73], v[54:57]
	s_waitcnt lgkmcnt(4)
	v_mfma_f32_16x16x128_f8f6f4 v[58:61], v[162:169], v[66:73], v[58:61]
	v_mfma_f32_16x16x128_f8f6f4 v[50:53], v[170:177], v[66:73], v[50:53]
	v_mfma_f32_16x16x128_f8f6f4 v[238:241], v[170:177], v[74:81], v[34:37]
	v_mfma_f32_16x16x128_f8f6f4 v[42:45], v[162:169], v[74:81], v[42:45]
	v_mfma_f32_16x16x128_f8f6f4 v[202:205], v[154:161], v[74:81], v[38:41]
	s_waitcnt lgkmcnt(2)
	v_mfma_f32_16x16x128_f8f6f4 v[46:49], v[146:153], v[74:81], v[46:49]
	v_mfma_f32_16x16x128_f8f6f4 v[206:209], v[146:153], v[82:89], v[30:33]
	s_waitcnt lgkmcnt(0)
	v_mfma_f32_16x16x128_f8f6f4 v[226:229], v[154:161], v[82:89], v[22:25]
	v_mfma_f32_16x16x128_f8f6f4 v[242:245], v[162:169], v[82:89], v[26:29]
	v_mfma_f32_16x16x128_f8f6f4 v[246:249], v[170:177], v[82:89], v[18:21]
	v_mfma_f32_16x16x128_f8f6f4 v[130:133], v[170:177], v[90:97], v[2:5]
	v_mfma_f32_16x16x128_f8f6f4 v[250:253], v[162:169], v[90:97], v[10:13]
	v_mfma_f32_16x16x128_f8f6f4 v[234:237], v[154:161], v[90:97], v[6:9]
	v_mfma_f32_16x16x128_f8f6f4 v[230:233], v[146:153], v[90:97], v[14:17]
	s_setprio 0
	s_barrier
	s_nop 4
	ds_read_b128 v[2:5], v141
	ds_read_b128 v[6:9], v141 offset:1024
	ds_read_b128 v[146:149], v141 offset:2048
	ds_read_b128 v[150:153], v141 offset:3072
	ds_read_b128 v[154:157], v142
	ds_read_b128 v[158:161], v142 offset:1024
	ds_read_b128 v[162:165], v142 offset:2048
	ds_read_b128 v[166:169], v142 offset:3072
	s_mov_b32 m0, s50
	s_add_i32 s79, s76, 0x80000
	ds_read_b128 v[10:13], v140 offset:32768
	ds_read_b128 v[14:17], v140 offset:33792
	ds_read_b128 v[18:21], v140 offset:34816
	ds_read_b128 v[22:25], v140 offset:35840
	ds_read_b128 v[26:29], v140 offset:36864
	ds_read_b128 v[30:33], v140 offset:37888
	ds_read_b128 v[34:37], v140 offset:38912
	ds_read_b128 v[38:41], v140 offset:39936
	buffer_load_dwordx4 v136, s[16:19], s79 offen lds
	s_add_i32 s79, s76, 0xc0000
	s_mov_b32 m0, s51
	s_nop 0
	buffer_load_dwordx4 v136, s[16:19], s79 offen lds
	s_waitcnt vmcnt(8)
	s_waitcnt lgkmcnt(0)
	s_setprio 1
	s_waitcnt lgkmcnt(6)
	v_mfma_f32_16x16x128_f8f6f4 v[118:121], v[2:9], v[10:17], v[118:121]
	s_barrier
	v_mfma_f32_16x16x128_f8f6f4 v[114:117], v[146:153], v[10:17], v[114:117]
	s_waitcnt lgkmcnt(4)
	v_mfma_f32_16x16x128_f8f6f4 v[126:129], v[154:161], v[10:17], v[126:129]
	v_mfma_f32_16x16x128_f8f6f4 v[122:125], v[162:169], v[10:17], v[122:125]
	s_waitcnt lgkmcnt(2)
	v_mfma_f32_16x16x128_f8f6f4 v[98:101], v[162:169], v[18:25], v[98:101]
	v_mfma_f32_16x16x128_f8f6f4 v[106:109], v[154:161], v[18:25], v[106:109]
	s_waitcnt lgkmcnt(0)
	v_mfma_f32_16x16x128_f8f6f4 v[102:105], v[146:153], v[18:25], v[102:105]
	v_mfma_f32_16x16x128_f8f6f4 v[110:113], v[2:9], v[18:25], v[110:113]
	v_mfma_f32_16x16x128_f8f6f4 v[94:97], v[2:9], v[26:33], v[210:213]
	v_mfma_f32_16x16x128_f8f6f4 v[86:89], v[146:153], v[26:33], v[214:217]
	v_mfma_f32_16x16x128_f8f6f4 v[90:93], v[154:161], v[26:33], v[178:181]
	v_mfma_f32_16x16x128_f8f6f4 v[82:85], v[162:169], v[26:33], v[182:185]
	v_mfma_f32_16x16x128_f8f6f4 v[66:69], v[162:169], v[34:41], v[190:193]
	v_mfma_f32_16x16x128_f8f6f4 v[74:77], v[154:161], v[34:41], v[186:189]
	v_mfma_f32_16x16x128_f8f6f4 v[70:73], v[146:153], v[34:41], v[222:225]
	v_mfma_f32_16x16x128_f8f6f4 v[78:81], v[2:9], v[34:41], v[218:221]
	s_setprio 0
	s_barrier
	s_mov_b32 m0, s54
	s_or_b32 s79, s78, 0x80
	ds_read_b128 v[170:173], v140 offset:49152
	ds_read_b128 v[174:177], v140 offset:50176
	ds_read_b128 v[178:181], v140 offset:51200
	ds_read_b128 v[182:185], v140 offset:52224
	ds_read_b128 v[186:189], v140 offset:53248
	ds_read_b128 v[190:193], v140 offset:54272
	ds_read_b128 v[194:197], v140 offset:55296
	ds_read_b128 v[198:201], v140 offset:56320
	buffer_load_dwordx4 v137, s[12:15], s79 offen lds
	s_add_i32 s79, s78, 0x40080
	s_mov_b32 m0, s55
	s_add_i32 s76, s76, 0x40080
	buffer_load_dwordx4 v137, s[12:15], s79 offen lds
	s_add_i32 s79, s78, 0x80080
	s_mov_b32 m0, s58
	s_add_i32 s78, s78, 0xc0080
	buffer_load_dwordx4 v137, s[12:15], s79 offen lds
	s_mov_b32 m0, s59
	s_nop 0
	buffer_load_dwordx4 v137, s[12:15], s78 offen lds
	s_mov_b32 m0, s56
	s_nop 0
	buffer_load_dwordx4 v136, s[16:19], s77 offen lds
	s_mov_b32 m0, s57
	s_nop 0
	buffer_load_dwordx4 v136, s[16:19], s76 offen lds
	s_waitcnt vmcnt(8)
	s_waitcnt lgkmcnt(0)
	s_setprio 1
	s_waitcnt lgkmcnt(6)
	v_mfma_f32_16x16x128_f8f6f4 v[62:65], v[2:9], v[170:177], v[62:65]
	s_barrier
	v_mfma_f32_16x16x128_f8f6f4 v[46:49], v[2:9], v[178:185], v[46:49]
	s_waitcnt lgkmcnt(4)
	v_mfma_f32_16x16x128_f8f6f4 v[30:33], v[2:9], v[186:193], v[206:209]
	v_mfma_f32_16x16x128_f8f6f4 v[14:17], v[2:9], v[194:201], v[230:233]
	s_waitcnt lgkmcnt(2)
	v_mfma_f32_16x16x128_f8f6f4 v[6:9], v[146:153], v[194:201], v[234:237]
	v_mfma_f32_16x16x128_f8f6f4 v[22:25], v[146:153], v[186:193], v[226:229]
	s_waitcnt lgkmcnt(0)
	v_mfma_f32_16x16x128_f8f6f4 v[38:41], v[146:153], v[178:185], v[202:205]
	v_mfma_f32_16x16x128_f8f6f4 v[54:57], v[146:153], v[170:177], v[54:57]
	v_mfma_f32_16x16x128_f8f6f4 v[58:61], v[154:161], v[170:177], v[58:61]
	v_mfma_f32_16x16x128_f8f6f4 v[42:45], v[154:161], v[178:185], v[42:45]
	v_mfma_f32_16x16x128_f8f6f4 v[26:29], v[154:161], v[186:193], v[242:245]
	v_mfma_f32_16x16x128_f8f6f4 v[10:13], v[154:161], v[194:201], v[250:253]
	v_mfma_f32_16x16x128_f8f6f4 v[2:5], v[162:169], v[194:201], v[130:133]
	v_mfma_f32_16x16x128_f8f6f4 v[18:21], v[162:169], v[186:193], v[246:249]
	v_mfma_f32_16x16x128_f8f6f4 v[34:37], v[162:169], v[178:185], v[238:241]
	v_mfma_f32_16x16x128_f8f6f4 v[50:53], v[162:169], v[170:177], v[50:53]
	s_setprio 0
	s_barrier
	s_add_i32 s75, s75, 2
	s_addk_i32 s73, 0x100
	s_addk_i32 s74, 0x100
	s_cmp_ge_i32 s75, s25
	s_cbranch_scc0 .LBB0_1420
	s_and_b64 vcc, exec, s[44:45]
	s_cbranch_vccz .LBB0_1423

.LBB0_1567:
	ds_read_b128 v[134:137], v225
	ds_read_b128 v[138:141], v225 offset:1024
	ds_read_b128 v[142:145], v225 offset:2048
	ds_read_b128 v[146:149], v225 offset:3072
	ds_read_b128 v[150:153], v226
	ds_read_b128 v[154:157], v226 offset:1024
	ds_read_b128 v[158:161], v226 offset:2048
	ds_read_b128 v[162:165], v226 offset:3072
	s_add_i32 s18, s8, 0xffdfc080
	s_cmp_eq_u32 s71, s55
	s_cselect_b32 s56, s6, s18
	s_cselect_b32 s91, s7, s9
	s_or_b32 s57, s56, 0x80
	s_add_i32 s18, s8, 0xfff54000
	s_mov_b32 m0, s72
	ds_read_b128 v[166:169], v227
	ds_read_b128 v[170:173], v227 offset:1024
	ds_read_b128 v[174:177], v227 offset:2048
	ds_read_b128 v[178:181], v227 offset:3072
	ds_read_b128 v[182:185], v227 offset:4096
	ds_read_b128 v[186:189], v227 offset:5120
	ds_read_b128 v[190:193], v227 offset:6144
	ds_read_b128 v[194:197], v227 offset:7168
	buffer_load_dwordx4 v223, s[12:15], s18 offen lds
	s_mov_b32 m0, s75
	s_nop 0
	buffer_load_dwordx4 v223, s[12:15], s8 offen lds
	s_waitcnt vmcnt(8)
	s_waitcnt lgkmcnt(0)
	s_setprio 1
	s_waitcnt lgkmcnt(6)
	v_mfma_f32_16x16x128_f8f6f4 v[126:129], v[134:141], v[166:173], v[126:129]
	s_barrier
	v_mfma_f32_16x16x128_f8f6f4 v[122:125], v[142:149], v[166:173], v[122:125]
	s_waitcnt lgkmcnt(4)
	v_mfma_f32_16x16x128_f8f6f4 v[110:113], v[150:157], v[166:173], v[110:113]
	v_mfma_f32_16x16x128_f8f6f4 v[102:105], v[158:165], v[166:173], v[102:105]
	s_waitcnt lgkmcnt(2)
	v_mfma_f32_16x16x128_f8f6f4 v[170:173], v[158:165], v[174:181], v[86:89]
	v_mfma_f32_16x16x128_f8f6f4 v[166:169], v[150:157], v[174:181], v[94:97]
	v_mfma_f32_16x16x128_f8f6f4 v[114:117], v[142:149], v[174:181], v[114:117]
	v_mfma_f32_16x16x128_f8f6f4 v[118:121], v[134:141], v[174:181], v[118:121]
	s_waitcnt lgkmcnt(0)
	v_mfma_f32_16x16x128_f8f6f4 v[106:109], v[134:141], v[182:189], v[106:109]
	v_mfma_f32_16x16x128_f8f6f4 v[98:101], v[142:149], v[182:189], v[98:101]
	v_mfma_f32_16x16x128_f8f6f4 v[174:177], v[150:157], v[182:189], v[78:81]
	v_mfma_f32_16x16x128_f8f6f4 v[178:181], v[158:165], v[182:189], v[74:77]
	v_mfma_f32_16x16x128_f8f6f4 v[186:189], v[158:165], v[190:197], v[66:69]
	v_mfma_f32_16x16x128_f8f6f4 v[182:185], v[150:157], v[190:197], v[70:73]
	v_mfma_f32_16x16x128_f8f6f4 v[202:205], v[142:149], v[190:197], v[82:85]
	v_mfma_f32_16x16x128_f8f6f4 v[198:201], v[134:141], v[190:197], v[90:93]
	s_setprio 0
	s_barrier
	s_mov_b32 m0, s27
	s_mov_b32 s18, s14
	s_mov_b32 s19, s15
	s_nop 1
	ds_read_b128 v[66:69], v227 offset:16384
	ds_read_b128 v[70:73], v227 offset:17408
	ds_read_b128 v[74:77], v227 offset:18432
	ds_read_b128 v[78:81], v227 offset:19456
	ds_read_b128 v[82:85], v227 offset:20480
	ds_read_b128 v[86:89], v227 offset:21504
	ds_read_b128 v[90:93], v227 offset:22528
	ds_read_b128 v[94:97], v227 offset:23552
	buffer_load_dwordx4 v224, s[16:19], s91 offen lds
	s_add_i32 s92, s91, 0xac000
	s_mov_b32 m0, s30
	s_nop 0
	buffer_load_dwordx4 v224, s[16:19], s92 offen lds
	s_add_i32 s92, s91, 0x158000
	s_mov_b32 m0, s31
	s_nop 0
	buffer_load_dwordx4 v224, s[16:19], s92 offen lds
	s_add_i32 s92, s91, 0x204000
	s_mov_b32 m0, s51
	s_nop 0
	buffer_load_dwordx4 v224, s[16:19], s92 offen lds
	s_mov_b32 m0, s25
	s_add_i32 s92, s56, 0xac000
	buffer_load_dwordx4 v223, s[12:15], s56 offen lds
	s_mov_b32 m0, s58
	s_nop 0
	buffer_load_dwordx4 v223, s[12:15], s92 offen lds
	s_waitcnt vmcnt(8)
	s_waitcnt lgkmcnt(0)
	s_setprio 1
	s_waitcnt lgkmcnt(6)
	v_mfma_f32_16x16x128_f8f6f4 v[62:65], v[134:141], v[66:73], v[62:65]
	s_barrier
	v_mfma_f32_16x16x128_f8f6f4 v[58:61], v[142:149], v[66:73], v[58:61]
	s_waitcnt lgkmcnt(4)
	v_mfma_f32_16x16x128_f8f6f4 v[214:217], v[150:157], v[66:73], v[46:49]
	v_mfma_f32_16x16x128_f8f6f4 v[218:221], v[158:165], v[66:73], v[38:41]
	s_waitcnt lgkmcnt(2)
	v_mfma_f32_16x16x128_f8f6f4 v[238:241], v[158:165], v[74:81], v[22:25]
	v_mfma_f32_16x16x128_f8f6f4 v[234:237], v[150:157], v[74:81], v[30:33]
	s_waitcnt lgkmcnt(0)
	v_mfma_f32_16x16x128_f8f6f4 v[50:53], v[142:149], v[74:81], v[50:53]
	v_mfma_f32_16x16x128_f8f6f4 v[54:57], v[134:141], v[74:81], v[54:57]
	v_mfma_f32_16x16x128_f8f6f4 v[190:193], v[134:141], v[82:89], v[42:45]
	v_mfma_f32_16x16x128_f8f6f4 v[194:197], v[142:149], v[82:89], v[34:37]
	v_mfma_f32_16x16x128_f8f6f4 v[242:245], v[150:157], v[82:89], v[14:17]
	v_mfma_f32_16x16x128_f8f6f4 v[246:249], v[158:165], v[82:89], v[10:13]
	v_mfma_f32_16x16x128_f8f6f4 v[130:133], v[158:165], v[90:97], v[2:5]
	v_mfma_f32_16x16x128_f8f6f4 v[250:253], v[150:157], v[90:97], v[6:9]
	v_mfma_f32_16x16x128_f8f6f4 v[210:213], v[142:149], v[90:97], v[18:21]
	v_mfma_f32_16x16x128_f8f6f4 v[206:209], v[134:141], v[90:97], v[26:29]
	s_setprio 0
	s_barrier
	s_nop 4
	ds_read_b128 v[2:5], v228
	ds_read_b128 v[6:9], v228 offset:1024
	ds_read_b128 v[10:13], v228 offset:2048
	ds_read_b128 v[14:17], v228 offset:3072
	ds_read_b128 v[134:137], v229
	ds_read_b128 v[138:141], v229 offset:1024
	ds_read_b128 v[142:145], v229 offset:2048
	ds_read_b128 v[146:149], v229 offset:3072
	s_mov_b32 m0, s59
	s_add_i32 s92, s56, 0x158000
	ds_read_b128 v[18:21], v227 offset:32768
	ds_read_b128 v[22:25], v227 offset:33792
	ds_read_b128 v[26:29], v227 offset:34816
	ds_read_b128 v[30:33], v227 offset:35840
	ds_read_b128 v[34:37], v227 offset:36864
	ds_read_b128 v[38:41], v227 offset:37888
	ds_read_b128 v[42:45], v227 offset:38912
	ds_read_b128 v[46:49], v227 offset:39936
	buffer_load_dwordx4 v223, s[12:15], s92 offen lds
	s_add_i32 s92, s56, 0x204000
	s_mov_b32 m0, s60
	s_nop 0
	buffer_load_dwordx4 v223, s[12:15], s92 offen lds
	s_waitcnt vmcnt(8)
	s_waitcnt lgkmcnt(0)
	s_setprio 1
	s_waitcnt lgkmcnt(6)
	v_mfma_f32_16x16x128_f8f6f4 v[126:129], v[2:9], v[18:25], v[126:129]
	s_barrier
	v_mfma_f32_16x16x128_f8f6f4 v[122:125], v[10:17], v[18:25], v[122:125]
	s_waitcnt lgkmcnt(4)
	v_mfma_f32_16x16x128_f8f6f4 v[110:113], v[134:141], v[18:25], v[110:113]
	v_mfma_f32_16x16x128_f8f6f4 v[102:105], v[142:149], v[18:25], v[102:105]
	s_waitcnt lgkmcnt(2)
	v_mfma_f32_16x16x128_f8f6f4 v[86:89], v[142:149], v[26:33], v[170:173]
	v_mfma_f32_16x16x128_f8f6f4 v[94:97], v[134:141], v[26:33], v[166:169]
	s_waitcnt lgkmcnt(0)
	v_mfma_f32_16x16x128_f8f6f4 v[114:117], v[10:17], v[26:33], v[114:117]
	v_mfma_f32_16x16x128_f8f6f4 v[118:121], v[2:9], v[26:33], v[118:121]
	v_mfma_f32_16x16x128_f8f6f4 v[106:109], v[2:9], v[34:41], v[106:109]
	v_mfma_f32_16x16x128_f8f6f4 v[98:101], v[10:17], v[34:41], v[98:101]
	v_mfma_f32_16x16x128_f8f6f4 v[78:81], v[134:141], v[34:41], v[174:177]
	v_mfma_f32_16x16x128_f8f6f4 v[74:77], v[142:149], v[34:41], v[178:181]
	v_mfma_f32_16x16x128_f8f6f4 v[66:69], v[142:149], v[42:49], v[186:189]
	v_mfma_f32_16x16x128_f8f6f4 v[70:73], v[134:141], v[42:49], v[182:185]
	v_mfma_f32_16x16x128_f8f6f4 v[82:85], v[10:17], v[42:49], v[202:205]
	v_mfma_f32_16x16x128_f8f6f4 v[90:93], v[2:9], v[42:49], v[198:201]
	s_setprio 0
	s_barrier
	s_mov_b32 m0, s63
	s_or_b32 s92, s91, 0x80
	ds_read_b128 v[150:153], v227 offset:49152
	ds_read_b128 v[154:157], v227 offset:50176
	ds_read_b128 v[158:161], v227 offset:51200
	ds_read_b128 v[162:165], v227 offset:52224
	ds_read_b128 v[166:169], v227 offset:53248
	ds_read_b128 v[170:173], v227 offset:54272
	ds_read_b128 v[174:177], v227 offset:55296
	ds_read_b128 v[178:181], v227 offset:56320
	buffer_load_dwordx4 v224, s[16:19], s92 offen lds
	s_add_i32 s92, s91, 0xac080
	s_mov_b32 m0, s64
	s_add_i32 s56, s56, 0xac080
	buffer_load_dwordx4 v224, s[16:19], s92 offen lds
	s_add_i32 s92, s91, 0x158080
	s_mov_b32 m0, s67
	s_add_i32 s91, s91, 0x204080
	buffer_load_dwordx4 v224, s[16:19], s92 offen lds
	s_mov_b32 m0, s68
	s_nop 0
	buffer_load_dwordx4 v224, s[16:19], s91 offen lds
	s_mov_b32 m0, s65
	s_nop 0
	buffer_load_dwordx4 v223, s[12:15], s57 offen lds
	s_mov_b32 m0, s66
	s_nop 0
	buffer_load_dwordx4 v223, s[12:15], s56 offen lds
	s_waitcnt vmcnt(8)
	s_waitcnt lgkmcnt(0)
	s_setprio 1
	s_waitcnt lgkmcnt(6)
	v_mfma_f32_16x16x128_f8f6f4 v[62:65], v[2:9], v[150:157], v[62:65]
	s_barrier
	v_mfma_f32_16x16x128_f8f6f4 v[54:57], v[2:9], v[158:165], v[54:57]
	s_waitcnt lgkmcnt(4)
	v_mfma_f32_16x16x128_f8f6f4 v[42:45], v[2:9], v[166:173], v[190:193]
	v_mfma_f32_16x16x128_f8f6f4 v[26:29], v[2:9], v[174:181], v[206:209]
	s_waitcnt lgkmcnt(2)
	v_mfma_f32_16x16x128_f8f6f4 v[18:21], v[10:17], v[174:181], v[210:213]
	v_mfma_f32_16x16x128_f8f6f4 v[34:37], v[10:17], v[166:173], v[194:197]
	s_waitcnt lgkmcnt(0)
	v_mfma_f32_16x16x128_f8f6f4 v[50:53], v[10:17], v[158:165], v[50:53]
	v_mfma_f32_16x16x128_f8f6f4 v[58:61], v[10:17], v[150:157], v[58:61]
	v_mfma_f32_16x16x128_f8f6f4 v[46:49], v[134:141], v[150:157], v[214:217]
	v_mfma_f32_16x16x128_f8f6f4 v[30:33], v[134:141], v[158:165], v[234:237]
	v_mfma_f32_16x16x128_f8f6f4 v[14:17], v[134:141], v[166:173], v[242:245]
	v_mfma_f32_16x16x128_f8f6f4 v[6:9], v[134:141], v[174:181], v[250:253]
	v_mfma_f32_16x16x128_f8f6f4 v[2:5], v[142:149], v[174:181], v[130:133]
	v_mfma_f32_16x16x128_f8f6f4 v[10:13], v[142:149], v[166:173], v[246:249]
	v_mfma_f32_16x16x128_f8f6f4 v[22:25], v[142:149], v[158:165], v[238:241]
	v_mfma_f32_16x16x128_f8f6f4 v[38:41], v[142:149], v[150:157], v[218:221]
	s_setprio 0
	s_barrier
	s_add_i32 s55, s55, 2
	s_addk_i32 s8, 0x100
	s_addk_i32 s9, 0x100
	s_cmp_ge_i32 s55, s3
	s_cbranch_scc0 .LBB0_1567
	v_pk_mul_f32 v[208:209], v[128:129], s[50:51] op_sel_hi:[1,0]
	v_pk_mul_f32 v[210:211], v[126:127], s[50:51] op_sel_hi:[1,0]
	v_pk_mul_f32 v[212:213], v[124:125], s[50:51] op_sel_hi:[1,0]
	v_pk_mul_f32 v[122:123], v[122:123], s[50:51] op_sel_hi:[1,0]
	v_pk_mul_f32 v[220:221], v[112:113], s[50:51] op_sel_hi:[1,0]
	v_pk_mul_f32 v[218:219], v[110:111], s[50:51] op_sel_hi:[1,0]
	v_pk_mul_f32 v[216:217], v[104:105], s[50:51] op_sel_hi:[1,0]
	v_pk_mul_f32 v[214:215], v[102:103], s[50:51] op_sel_hi:[1,0]
	v_pk_mul_f32 v[206:207], v[120:121], s[50:51] op_sel_hi:[1,0]
	v_pk_mul_f32 v[146:147], v[118:119], s[50:51] op_sel_hi:[1,0]
	v_pk_mul_f32 v[204:205], v[116:117], s[50:51] op_sel_hi:[1,0]
	v_pk_mul_f32 v[144:145], v[114:115], s[50:51] op_sel_hi:[1,0]
	v_pk_mul_f32 v[148:149], v[96:97], s[50:51] op_sel_hi:[1,0]
	v_pk_mul_f32 v[154:155], v[94:95], s[50:51] op_sel_hi:[1,0]
	v_pk_mul_f32 v[202:203], v[88:89], s[50:51] op_sel_hi:[1,0]
	v_pk_mul_f32 v[200:201], v[86:87], s[50:51] op_sel_hi:[1,0]
	v_pk_mul_f32 v[198:199], v[108:109], s[50:51] op_sel_hi:[1,0]
	v_pk_mul_f32 v[152:153], v[106:107], s[50:51] op_sel_hi:[1,0]
	v_pk_mul_f32 v[196:197], v[100:101], s[50:51] op_sel_hi:[1,0]
	v_pk_mul_f32 v[150:151], v[98:99], s[50:51] op_sel_hi:[1,0]
	v_pk_mul_f32 v[156:157], v[80:81], s[50:51] op_sel_hi:[1,0]
	v_pk_mul_f32 v[162:163], v[78:79], s[50:51] op_sel_hi:[1,0]
	v_pk_mul_f32 v[194:195], v[76:77], s[50:51] op_sel_hi:[1,0]
	v_pk_mul_f32 v[192:193], v[74:75], s[50:51] op_sel_hi:[1,0]
	v_pk_mul_f32 v[190:191], v[92:93], s[50:51] op_sel_hi:[1,0]
	v_pk_mul_f32 v[160:161], v[90:91], s[50:51] op_sel_hi:[1,0]
	v_pk_mul_f32 v[188:189], v[84:85], s[50:51] op_sel_hi:[1,0]
	v_pk_mul_f32 v[158:159], v[82:83], s[50:51] op_sel_hi:[1,0]
	v_pk_mul_f32 v[164:165], v[72:73], s[50:51] op_sel_hi:[1,0]
	v_pk_mul_f32 v[170:171], v[70:71], s[50:51] op_sel_hi:[1,0]
	v_pk_mul_f32 v[186:187], v[68:69], s[50:51] op_sel_hi:[1,0]
	v_pk_mul_f32 v[184:185], v[66:67], s[50:51] op_sel_hi:[1,0]
	v_pk_mul_f32 v[182:183], v[64:65], s[50:51] op_sel_hi:[1,0]
	v_pk_mul_f32 v[168:169], v[62:63], s[50:51] op_sel_hi:[1,0]
	v_pk_mul_f32 v[180:181], v[60:61], s[50:51] op_sel_hi:[1,0]
	v_pk_mul_f32 v[166:167], v[58:59], s[50:51] op_sel_hi:[1,0]
	v_pk_mul_f32 v[172:173], v[48:49], s[50:51] op_sel_hi:[1,0]
	v_pk_mul_f32 v[178:179], v[46:47], s[50:51] op_sel_hi:[1,0]
	v_pk_mul_f32 v[176:177], v[40:41], s[50:51] op_sel_hi:[1,0]
	v_pk_mul_f32 v[174:175], v[38:39], s[50:51] op_sel_hi:[1,0]
	v_pk_mul_f32 v[142:143], v[56:57], s[50:51] op_sel_hi:[1,0]
	v_pk_mul_f32 v[140:141], v[54:55], s[50:51] op_sel_hi:[1,0]
	v_pk_mul_f32 v[138:139], v[52:53], s[50:51] op_sel_hi:[1,0]
	v_pk_mul_f32 v[134:135], v[50:51], s[50:51] op_sel_hi:[1,0]
	v_pk_mul_f32 v[136:137], v[32:33], s[50:51] op_sel_hi:[1,0]
	v_pk_mul_f32 v[128:129], v[30:31], s[50:51] op_sel_hi:[1,0]
	v_pk_mul_f32 v[126:127], v[24:25], s[50:51] op_sel_hi:[1,0]
	v_pk_mul_f32 v[124:125], v[22:23], s[50:51] op_sel_hi:[1,0]
	v_pk_mul_f32 v[102:103], v[44:45], s[50:51] op_sel_hi:[1,0]
	v_pk_mul_f32 v[100:101], v[42:43], s[50:51] op_sel_hi:[1,0]
	v_pk_mul_f32 v[98:99], v[36:37], s[50:51] op_sel_hi:[1,0]
	v_pk_mul_f32 v[94:95], v[34:35], s[50:51] op_sel_hi:[1,0]
	v_pk_mul_f32 v[96:97], v[16:17], s[50:51] op_sel_hi:[1,0]
	v_pk_mul_f32 v[92:93], v[14:15], s[50:51] op_sel_hi:[1,0]
	v_pk_mul_f32 v[90:91], v[12:13], s[50:51] op_sel_hi:[1,0]
	v_pk_mul_f32 v[88:89], v[10:11], s[50:51] op_sel_hi:[1,0]
	v_pk_mul_f32 v[86:87], v[28:29], s[50:51] op_sel_hi:[1,0]
	v_pk_mul_f32 v[84:85], v[26:27], s[50:51] op_sel_hi:[1,0]
	v_pk_mul_f32 v[82:83], v[20:21], s[50:51] op_sel_hi:[1,0]
	v_pk_mul_f32 v[78:79], v[18:19], s[50:51] op_sel_hi:[1,0]
	v_pk_mul_f32 v[80:81], v[8:9], s[50:51] op_sel_hi:[1,0]
	v_pk_mul_f32 v[76:77], v[6:7], s[50:51] op_sel_hi:[1,0]
	v_pk_mul_f32 v[74:75], v[4:5], s[50:51] op_sel_hi:[1,0]
	v_pk_mul_f32 v[72:73], v[2:3], s[50:51] op_sel_hi:[1,0]
	s_and_b64 vcc, exec, s[48:49]
	s_cbranch_vccz .LBB0_1570
